# grid barrier: L1 invalidate (buffer_inv sc1) issued at arrival instead of after the release flag (overlaps with polling); no loads are issued by a CU between arrival and release
# speedup vs baseline: 1.0101x; 1.0087x over previous
; __device__ __forceinline__ unsigned xb_ld(unsigned* p)              { return __hip_atomic_load(p, __ATOMIC_RELAXED, __HIP_MEMORY_SCOPE_AGENT); }
; __device__ __forceinline__ unsigned xb_add(unsigned* p, unsigned v) { return __hip_atomic_fetch_add(p, v, __ATOMIC_RELAXED, __HIP_MEMORY_SCOPE_AGENT); }
; #define XB_SPIN(cond, bar) do { unsigned _sp = 0; while (cond) { __builtin_amdgcn_s_sleep(1); \
;     if ((++_sp & 255u) == 0u) { if (xb_ld(&(bar)[XB_TMO])) break; if (_sp > XB_SPIN_CAP) { atomicAdd(&(bar)[XB_TMO], 1u); break; } } } } while (0)
; __device__ __forceinline__ void xcd_barrier(const XcdBarrier& b, bool leader) {
;     ...
;         if (nloc == 0u) { xcd_barrier_complete(bar, b.x, nloc, nx); b.st[0] = nloc; b.st[1] = nx; }
;         const unsigned old = xb_add(&bar[XB_XSUB(b.x)], 1u);
;         const unsigned gen = old / nloc;
;         if (old + 1u == (gen + 1u) * nloc) {
;             __builtin_amdgcn_fence(__ATOMIC_RELEASE, "agent");
;             asm volatile("s_waitcnt vmcnt(0)" ::: "memory");
;             const unsigned og = xb_add(&bar[XB_TOP], 1u);
;             const unsigned tg = og / nx;
;             if (og + 1u == (tg + 1u) * nx) xb_add(&bar[XB_TOPGEN], 1u);
;             else XB_SPIN(xb_ld(&bar[XB_TOPGEN]) == tg, bar);
;             __builtin_amdgcn_fence(__ATOMIC_ACQUIRE, "agent");
;             xb_add(&bar[XB_XGEN(b.x)], 1u);
;             asm volatile("s_waitcnt vmcnt(0)" ::: "memory");
;         } else {
;             XB_SPIN(xb_ld(&bar[XB_XGEN(b.x)]) == gen, bar);
.LBB0_144:
	s_or_b64 exec, exec, s[10:11]
	v_cvt_f32_u32_e32 v4, v2
	s_waitcnt vmcnt(0)
	v_readfirstlane_b32 s8, v3
	v_sub_u32_e32 v3, 0, v2
	v_rcp_iflag_f32_e32 v4, v4
	v_add_u32_e32 v5, s8, v1
	v_mul_f32_e32 v4, 0x4f7ffffe, v4
	v_cvt_u32_f32_e32 v4, v4
	v_mul_lo_u32 v1, v3, v4
	v_mul_hi_u32 v1, v4, v1
	v_add_u32_e32 v1, v4, v1
	v_mul_hi_u32 v1, v5, v1
	v_mul_lo_u32 v3, v1, v2
	v_sub_u32_e32 v3, v5, v3
	v_add_u32_e32 v4, 1, v1
	v_cmp_ge_u32_e32 vcc, v3, v2
	s_nop 1
	v_cndmask_b32_e32 v1, v1, v4, vcc
	v_sub_u32_e32 v4, v3, v2
	v_cndmask_b32_e32 v3, v3, v4, vcc
	v_add_u32_e32 v4, 1, v1
	v_cmp_ge_u32_e32 vcc, v3, v2
	v_add_u32_e32 v3, 1, v5
	s_nop 0
	v_cndmask_b32_e32 v1, v1, v4, vcc
	v_mul_lo_u32 v4, v2, v1
	v_add_u32_e32 v2, v4, v2
	v_cmp_ne_u32_e32 vcc, v3, v2
	s_and_saveexec_b64 s[8:9], vcc
	s_xor_b64 s[8:9], exec, s[8:9]
	s_cbranch_execz .LBB0_158
	buffer_inv sc1
	s_waitcnt lgkmcnt(0)
	v_mov_b32_e32 v0, 0x2000
	global_load_dword v0, v0, s[6:7] offset:1024 sc1
	s_add_u32 s14, s6, 0x2400
	s_addc_u32 s15, s7, 0
	s_waitcnt vmcnt(0)
	v_cmp_eq_u32_e32 vcc, v0, v1
	s_and_saveexec_b64 s[10:11], vcc
	s_cbranch_execz .LBB0_157
	s_mov_b32 s13, 1
	s_mov_b64 s[16:17], 0
	v_mov_b32_e32 v0, 0
	s_branch .LBB0_148

; __device__ __forceinline__ unsigned xb_ld(unsigned* p)              { return __hip_atomic_load(p, __ATOMIC_RELAXED, __HIP_MEMORY_SCOPE_AGENT); }
; #define XB_SPIN(cond, bar) do { unsigned _sp = 0; while (cond) { __builtin_amdgcn_s_sleep(1); \
;     if ((++_sp & 255u) == 0u) { if (xb_ld(&(bar)[XB_TMO])) break; if (_sp > XB_SPIN_CAP) { atomicAdd(&(bar)[XB_TMO], 1u); break; } } } } while (0)
; __device__ __forceinline__ void xcd_barrier(const XcdBarrier& b, bool leader) {
;     ...
;             XB_SPIN(xb_ld(&bar[XB_XGEN(b.x)]) == gen, bar);
;             __builtin_amdgcn_fence(__ATOMIC_ACQUIRE, "agent");
;             asm volatile("s_waitcnt vmcnt(0)" ::: "memory");
.LBB0_157:
	s_or_b64 exec, exec, s[10:11]
	s_waitcnt vmcnt(0)
	s_waitcnt vmcnt(0)

; __device__ __forceinline__ unsigned xb_ld(unsigned* p)              { return __hip_atomic_load(p, __ATOMIC_RELAXED, __HIP_MEMORY_SCOPE_AGENT); }
; __device__ __forceinline__ unsigned xb_add(unsigned* p, unsigned v) { return __hip_atomic_fetch_add(p, v, __ATOMIC_RELAXED, __HIP_MEMORY_SCOPE_AGENT); }
; #define XB_SPIN(cond, bar) do { unsigned _sp = 0; while (cond) { __builtin_amdgcn_s_sleep(1); \
;     if ((++_sp & 255u) == 0u) { if (xb_ld(&(bar)[XB_TMO])) break; if (_sp > XB_SPIN_CAP) { atomicAdd(&(bar)[XB_TMO], 1u); break; } } } } while (0)
; __device__ __forceinline__ void xcd_barrier(const XcdBarrier& b, bool leader) {
;     ...
;             const unsigned og = xb_add(&bar[XB_TOP], 1u);
;             const unsigned tg = og / nx;
;             if (og + 1u == (tg + 1u) * nx) xb_add(&bar[XB_TOPGEN], 1u);
;             else XB_SPIN(xb_ld(&bar[XB_TOPGEN]) == tg, bar);
.LBB0_161:
	s_or_b64 exec, exec, s[10:11]
	buffer_inv sc1
	v_cvt_f32_u32_e32 v3, v0
	s_waitcnt vmcnt(0)
	v_readfirstlane_b32 s8, v2
	s_add_u32 s10, s76, 0x3500
	s_addc_u32 s11, s77, 0
	v_rcp_iflag_f32_e32 v3, v3
	v_add_u32_e32 v1, s8, v1
	v_add_u32_e32 v4, 1, v1
	s_mov_b64 s[14:15], -1
	v_mul_f32_e32 v2, 0x4f7ffffe, v3
	v_cvt_u32_f32_e32 v2, v2
	v_sub_u32_e32 v3, 0, v0
	v_mul_lo_u32 v3, v3, v2
	v_mul_hi_u32 v3, v2, v3
	v_add_u32_e32 v2, v2, v3
	v_mul_hi_u32 v2, v1, v2
	v_mul_lo_u32 v3, v2, v0
	v_sub_u32_e32 v1, v1, v3
	v_add_u32_e32 v5, 1, v2
	v_cmp_ge_u32_e32 vcc, v1, v0
	v_sub_u32_e32 v3, v1, v0
	s_nop 0
	v_cndmask_b32_e32 v2, v2, v5, vcc
	v_cndmask_b32_e32 v1, v1, v3, vcc
	v_add_u32_e32 v3, 1, v2
	v_cmp_ge_u32_e32 vcc, v1, v0
	s_nop 1
	v_cndmask_b32_e32 v2, v2, v3, vcc
	v_mul_lo_u32 v1, v0, v2
	v_add_u32_e32 v0, v1, v0
	v_cmp_ne_u32_e32 vcc, v4, v0
	v_mov_b64_e32 v[0:1], s[10:11]
	s_and_saveexec_b64 s[8:9], vcc
	s_cbranch_execz .LBB0_173
	v_mov_b32_e32 v0, 0
	global_load_dword v1, v0, s[10:11] sc1
	s_mov_b64 s[18:19], 0
	s_waitcnt vmcnt(0)
	v_cmp_eq_u32_e32 vcc, v1, v2
	s_and_saveexec_b64 s[16:17], vcc
	s_cbranch_execz .LBB0_172
	s_add_u32 s14, s76, 0x200
	s_addc_u32 s15, s77, 0
	s_mov_b32 s13, 1
	s_branch .LBB0_165

; __device__ __forceinline__ unsigned xb_add(unsigned* p, unsigned v) { return __hip_atomic_fetch_add(p, v, __ATOMIC_RELAXED, __HIP_MEMORY_SCOPE_AGENT); }
; __device__ __forceinline__ void xcd_barrier(const XcdBarrier& b, bool leader) {
;     ...
;             __builtin_amdgcn_fence(__ATOMIC_ACQUIRE, "agent");
;             xb_add(&bar[XB_XGEN(b.x)], 1u);
.LBB0_175:
	s_or_b64 exec, exec, s[8:9]
	s_mov_b64 s[8:9], exec
	v_mbcnt_lo_u32_b32 v0, s8, 0
	v_mbcnt_hi_u32_b32 v0, s9, v0
	v_cmp_eq_u32_e32 vcc, 0, v0
	s_waitcnt vmcnt(0)
	s_and_saveexec_b64 s[10:11], vcc
	s_cbranch_execz .LBB0_177
	s_bcnt1_i32_b64 s8, s[8:9]
	v_mov_b32_e32 v0, 0x2000
	v_mov_b32_e32 v1, s8
	global_atomic_add v0, v1, s[6:7] offset:1024

; __device__ __forceinline__ unsigned xb_ld(unsigned* p)              { return __hip_atomic_load(p, __ATOMIC_RELAXED, __HIP_MEMORY_SCOPE_AGENT); }
; __device__ __forceinline__ unsigned xb_add(unsigned* p, unsigned v) { return __hip_atomic_fetch_add(p, v, __ATOMIC_RELAXED, __HIP_MEMORY_SCOPE_AGENT); }
; #define XB_SPIN(cond, bar) do { unsigned _sp = 0; while (cond) { __builtin_amdgcn_s_sleep(1); \
;     if ((++_sp & 255u) == 0u) { if (xb_ld(&(bar)[XB_TMO])) break; if (_sp > XB_SPIN_CAP) { atomicAdd(&(bar)[XB_TMO], 1u); break; } } } } while (0)
; __device__ __forceinline__ void xcd_barrier(const XcdBarrier& b, bool leader) {
;     ...
;         if (nloc == 0u) { xcd_barrier_complete(bar, b.x, nloc, nx); b.st[0] = nloc; b.st[1] = nx; }
;         const unsigned old = xb_add(&bar[XB_XSUB(b.x)], 1u);
;         const unsigned gen = old / nloc;
;         if (old + 1u == (gen + 1u) * nloc) {
;             __builtin_amdgcn_fence(__ATOMIC_RELEASE, "agent");
;             asm volatile("s_waitcnt vmcnt(0)" ::: "memory");
;             const unsigned og = xb_add(&bar[XB_TOP], 1u);
;             const unsigned tg = og / nx;
;             if (og + 1u == (tg + 1u) * nx) xb_add(&bar[XB_TOPGEN], 1u);
;             else XB_SPIN(xb_ld(&bar[XB_TOPGEN]) == tg, bar);
;             __builtin_amdgcn_fence(__ATOMIC_ACQUIRE, "agent");
;             xb_add(&bar[XB_XGEN(b.x)], 1u);
;             asm volatile("s_waitcnt vmcnt(0)" ::: "memory");
;         } else {
;             XB_SPIN(xb_ld(&bar[XB_XGEN(b.x)]) == gen, bar);
.LBB0_363:
	s_or_b64 exec, exec, s[10:11]
	v_cvt_f32_u32_e32 v4, v2
	s_waitcnt vmcnt(0)
	v_readfirstlane_b32 s8, v3
	v_sub_u32_e32 v3, 0, v2
	v_rcp_iflag_f32_e32 v4, v4
	v_add_u32_e32 v5, s8, v1
	v_mul_f32_e32 v4, 0x4f7ffffe, v4
	v_cvt_u32_f32_e32 v4, v4
	v_mul_lo_u32 v1, v3, v4
	v_mul_hi_u32 v1, v4, v1
	v_add_u32_e32 v1, v4, v1
	v_mul_hi_u32 v1, v5, v1
	v_mul_lo_u32 v3, v1, v2
	v_sub_u32_e32 v3, v5, v3
	v_add_u32_e32 v4, 1, v1
	v_cmp_ge_u32_e32 vcc, v3, v2
	s_nop 1
	v_cndmask_b32_e32 v1, v1, v4, vcc
	v_sub_u32_e32 v4, v3, v2
	v_cndmask_b32_e32 v3, v3, v4, vcc
	v_add_u32_e32 v4, 1, v1
	v_cmp_ge_u32_e32 vcc, v3, v2
	v_add_u32_e32 v3, 1, v5
	s_nop 0
	v_cndmask_b32_e32 v1, v1, v4, vcc
	v_mul_lo_u32 v4, v2, v1
	v_add_u32_e32 v2, v4, v2
	v_cmp_ne_u32_e32 vcc, v3, v2
	s_and_saveexec_b64 s[8:9], vcc
	s_xor_b64 s[8:9], exec, s[8:9]
	s_cbranch_execz .LBB0_377
	buffer_inv sc1
	s_waitcnt lgkmcnt(0)
	v_mov_b32_e32 v0, 0x2000
	global_load_dword v0, v0, s[6:7] offset:1024 sc1
	s_add_u32 s12, s6, 0x2400
	s_addc_u32 s13, s7, 0
	s_waitcnt vmcnt(0)
	v_cmp_eq_u32_e32 vcc, v0, v1
	s_and_saveexec_b64 s[10:11], vcc
	s_cbranch_execz .LBB0_376
	s_mov_b32 s24, 1
	s_mov_b64 s[14:15], 0
	v_mov_b32_e32 v0, 0
	s_branch .LBB0_367

; __device__ __forceinline__ unsigned xb_ld(unsigned* p)              { return __hip_atomic_load(p, __ATOMIC_RELAXED, __HIP_MEMORY_SCOPE_AGENT); }
; __device__ __forceinline__ unsigned xb_add(unsigned* p, unsigned v) { return __hip_atomic_fetch_add(p, v, __ATOMIC_RELAXED, __HIP_MEMORY_SCOPE_AGENT); }
; #define XB_SPIN(cond, bar) do { unsigned _sp = 0; while (cond) { __builtin_amdgcn_s_sleep(1); \
;     if ((++_sp & 255u) == 0u) { if (xb_ld(&(bar)[XB_TMO])) break; if (_sp > XB_SPIN_CAP) { atomicAdd(&(bar)[XB_TMO], 1u); break; } } } } while (0)
; __device__ __forceinline__ void xcd_barrier(const XcdBarrier& b, bool leader) {
;     ...
;             const unsigned og = xb_add(&bar[XB_TOP], 1u);
;             const unsigned tg = og / nx;
;             if (og + 1u == (tg + 1u) * nx) xb_add(&bar[XB_TOPGEN], 1u);
;             else XB_SPIN(xb_ld(&bar[XB_TOPGEN]) == tg, bar);
.LBB0_380:
	s_or_b64 exec, exec, s[10:11]
	buffer_inv sc1
	v_cvt_f32_u32_e32 v3, v0
	s_waitcnt vmcnt(0)
	v_readfirstlane_b32 s8, v2
	s_add_u32 s10, s76, 0x3500
	s_addc_u32 s11, s77, 0
	v_rcp_iflag_f32_e32 v3, v3
	v_add_u32_e32 v1, s8, v1
	v_add_u32_e32 v4, 1, v1
	s_mov_b64 s[12:13], -1
	v_mul_f32_e32 v2, 0x4f7ffffe, v3
	v_cvt_u32_f32_e32 v2, v2
	v_sub_u32_e32 v3, 0, v0
	v_mul_lo_u32 v3, v3, v2
	v_mul_hi_u32 v3, v2, v3
	v_add_u32_e32 v2, v2, v3
	v_mul_hi_u32 v2, v1, v2
	v_mul_lo_u32 v3, v2, v0
	v_sub_u32_e32 v1, v1, v3
	v_add_u32_e32 v5, 1, v2
	v_cmp_ge_u32_e32 vcc, v1, v0
	v_sub_u32_e32 v3, v1, v0
	s_nop 0
	v_cndmask_b32_e32 v2, v2, v5, vcc
	v_cndmask_b32_e32 v1, v1, v3, vcc
	v_add_u32_e32 v3, 1, v2
	v_cmp_ge_u32_e32 vcc, v1, v0
	s_nop 1
	v_cndmask_b32_e32 v2, v2, v3, vcc
	v_mul_lo_u32 v1, v0, v2
	v_add_u32_e32 v0, v1, v0
	v_cmp_ne_u32_e32 vcc, v4, v0
	v_mov_b64_e32 v[0:1], s[10:11]
	s_and_saveexec_b64 s[8:9], vcc
	s_cbranch_execz .LBB0_392
	v_mov_b32_e32 v0, 0
	global_load_dword v1, v0, s[10:11] sc1
	s_mov_b64 s[16:17], 0
	s_waitcnt vmcnt(0)
	v_cmp_eq_u32_e32 vcc, v1, v2
	s_and_saveexec_b64 s[14:15], vcc
	s_cbranch_execz .LBB0_391
	s_add_u32 s12, s76, 0x200
	s_addc_u32 s13, s77, 0
	s_mov_b32 s26, 1
	s_branch .LBB0_384

; __device__ __forceinline__ unsigned xb_ld(unsigned* p)              { return __hip_atomic_load(p, __ATOMIC_RELAXED, __HIP_MEMORY_SCOPE_AGENT); }
; __device__ __forceinline__ unsigned xb_add(unsigned* p, unsigned v) { return __hip_atomic_fetch_add(p, v, __ATOMIC_RELAXED, __HIP_MEMORY_SCOPE_AGENT); }
; #define XB_SPIN(cond, bar) do { unsigned _sp = 0; while (cond) { __builtin_amdgcn_s_sleep(1); \
;     if ((++_sp & 255u) == 0u) { if (xb_ld(&(bar)[XB_TMO])) break; if (_sp > XB_SPIN_CAP) { atomicAdd(&(bar)[XB_TMO], 1u); break; } } } } while (0)
; __device__ __forceinline__ void xcd_barrier(const XcdBarrier& b, bool leader) {
;     ...
;         if (nloc == 0u) { xcd_barrier_complete(bar, b.x, nloc, nx); b.st[0] = nloc; b.st[1] = nx; }
;         const unsigned old = xb_add(&bar[XB_XSUB(b.x)], 1u);
;         const unsigned gen = old / nloc;
;         if (old + 1u == (gen + 1u) * nloc) {
;             __builtin_amdgcn_fence(__ATOMIC_RELEASE, "agent");
;             asm volatile("s_waitcnt vmcnt(0)" ::: "memory");
;             const unsigned og = xb_add(&bar[XB_TOP], 1u);
;             const unsigned tg = og / nx;
;             if (og + 1u == (tg + 1u) * nx) xb_add(&bar[XB_TOPGEN], 1u);
;             else XB_SPIN(xb_ld(&bar[XB_TOPGEN]) == tg, bar);
;             __builtin_amdgcn_fence(__ATOMIC_ACQUIRE, "agent");
;             xb_add(&bar[XB_XGEN(b.x)], 1u);
;             asm volatile("s_waitcnt vmcnt(0)" ::: "memory");
;         } else {
;             XB_SPIN(xb_ld(&bar[XB_XGEN(b.x)]) == gen, bar);
.LBB0_1428:
	s_or_b64 exec, exec, s[10:11]
	v_cvt_f32_u32_e32 v4, v2
	s_waitcnt vmcnt(0)
	v_readfirstlane_b32 s3, v3
	v_sub_u32_e32 v3, 0, v2
	v_rcp_iflag_f32_e32 v4, v4
	v_add_u32_e32 v5, s3, v1
	v_mul_f32_e32 v4, 0x4f7ffffe, v4
	v_cvt_u32_f32_e32 v4, v4
	v_mul_lo_u32 v1, v3, v4
	v_mul_hi_u32 v1, v4, v1
	v_add_u32_e32 v1, v4, v1
	v_mul_hi_u32 v1, v5, v1
	v_mul_lo_u32 v3, v1, v2
	v_sub_u32_e32 v3, v5, v3
	v_add_u32_e32 v4, 1, v1
	v_cmp_ge_u32_e32 vcc, v3, v2
	s_nop 1
	v_cndmask_b32_e32 v1, v1, v4, vcc
	v_sub_u32_e32 v4, v3, v2
	v_cndmask_b32_e32 v3, v3, v4, vcc
	v_add_u32_e32 v4, 1, v1
	v_cmp_ge_u32_e32 vcc, v3, v2
	v_add_u32_e32 v3, 1, v5
	s_nop 0
	v_cndmask_b32_e32 v1, v1, v4, vcc
	v_mul_lo_u32 v4, v2, v1
	v_add_u32_e32 v2, v4, v2
	v_cmp_ne_u32_e32 vcc, v3, v2
	s_and_saveexec_b64 s[8:9], vcc
	s_xor_b64 s[8:9], exec, s[8:9]
	s_cbranch_execz .LBB0_1446
	buffer_inv sc1
	s_waitcnt lgkmcnt(0)
	v_mov_b32_e32 v0, 0x2000
	global_load_dword v0, v0, s[6:7] offset:1024 sc1
	s_add_u32 s12, s6, 0x2400
	s_addc_u32 s13, s7, 0
	s_waitcnt vmcnt(0)
	v_cmp_eq_u32_e32 vcc, v0, v1
	s_and_saveexec_b64 s[10:11], vcc
	s_cbranch_execz .LBB0_1445
	s_mov_b32 s3, 1
	s_mov_b64 s[14:15], 0
	v_mov_b32_e32 v0, 0
	s_branch .LBB0_1432

; __device__ __forceinline__ unsigned xb_ld(unsigned* p)              { return __hip_atomic_load(p, __ATOMIC_RELAXED, __HIP_MEMORY_SCOPE_AGENT); }
; __device__ __forceinline__ unsigned xb_add(unsigned* p, unsigned v) { return __hip_atomic_fetch_add(p, v, __ATOMIC_RELAXED, __HIP_MEMORY_SCOPE_AGENT); }
; #define XB_SPIN(cond, bar) do { unsigned _sp = 0; while (cond) { __builtin_amdgcn_s_sleep(1); \
;     if ((++_sp & 255u) == 0u) { if (xb_ld(&(bar)[XB_TMO])) break; if (_sp > XB_SPIN_CAP) { atomicAdd(&(bar)[XB_TMO], 1u); break; } } } } while (0)
; __device__ __forceinline__ void xcd_barrier(const XcdBarrier& b, bool leader) {
;     ...
;             const unsigned og = xb_add(&bar[XB_TOP], 1u);
;             const unsigned tg = og / nx;
;             if (og + 1u == (tg + 1u) * nx) xb_add(&bar[XB_TOPGEN], 1u);
;             else XB_SPIN(xb_ld(&bar[XB_TOPGEN]) == tg, bar);
.LBB0_1449:
	s_or_b64 exec, exec, s[10:11]
	buffer_inv sc1
	v_cvt_f32_u32_e32 v3, v0
	s_waitcnt vmcnt(0)
	v_readfirstlane_b32 s3, v2
	s_add_u32 s10, s76, 0x3500
	s_addc_u32 s11, s77, 0
	v_rcp_iflag_f32_e32 v3, v3
	v_add_u32_e32 v1, s3, v1
	v_add_u32_e32 v4, 1, v1
	s_mov_b64 s[12:13], -1
	v_mul_f32_e32 v2, 0x4f7ffffe, v3
	v_cvt_u32_f32_e32 v2, v2
	v_sub_u32_e32 v3, 0, v0
	v_mul_lo_u32 v3, v3, v2
	v_mul_hi_u32 v3, v2, v3
	v_add_u32_e32 v2, v2, v3
	v_mul_hi_u32 v2, v1, v2
	v_mul_lo_u32 v3, v2, v0
	v_sub_u32_e32 v1, v1, v3
	v_add_u32_e32 v5, 1, v2
	v_cmp_ge_u32_e32 vcc, v1, v0
	v_sub_u32_e32 v3, v1, v0
	s_nop 0
	v_cndmask_b32_e32 v2, v2, v5, vcc
	v_cndmask_b32_e32 v1, v1, v3, vcc
	v_add_u32_e32 v3, 1, v2
	v_cmp_ge_u32_e32 vcc, v1, v0
	s_nop 1
	v_cndmask_b32_e32 v2, v2, v3, vcc
	v_mul_lo_u32 v1, v0, v2
	v_add_u32_e32 v0, v1, v0
	v_cmp_ne_u32_e32 vcc, v4, v0
	v_mov_b64_e32 v[0:1], s[10:11]
	s_and_saveexec_b64 s[8:9], vcc
	s_cbranch_execz .LBB0_1461
	v_mov_b32_e32 v0, 0
	global_load_dword v1, v0, s[10:11] sc1
	s_mov_b64 s[16:17], 0
	s_waitcnt vmcnt(0)
	v_cmp_eq_u32_e32 vcc, v1, v2
	s_and_saveexec_b64 s[14:15], vcc
	s_cbranch_execz .LBB0_1460
	s_add_u32 s12, s76, 0x200
	s_addc_u32 s13, s77, 0
	s_mov_b32 s3, 1
	s_branch .LBB0_1453

; __device__ __forceinline__ unsigned xb_add(unsigned* p, unsigned v) { return __hip_atomic_fetch_add(p, v, __ATOMIC_RELAXED, __HIP_MEMORY_SCOPE_AGENT); }
; __device__ __forceinline__ void xcd_barrier(const XcdBarrier& b, bool leader) {
;     ...
;             __builtin_amdgcn_fence(__ATOMIC_ACQUIRE, "agent");
;             xb_add(&bar[XB_XGEN(b.x)], 1u);
.LBB0_1463:
	s_or_b64 exec, exec, s[8:9]
	s_mov_b64 s[8:9], exec
	v_mbcnt_lo_u32_b32 v0, s8, 0
	v_mbcnt_hi_u32_b32 v0, s9, v0
	v_cmp_eq_u32_e32 vcc, 0, v0
	s_waitcnt vmcnt(0)
	s_and_saveexec_b64 s[10:11], vcc
	s_cbranch_execz .LBB0_1465
	s_bcnt1_i32_b64 s3, s[8:9]
	v_mov_b32_e32 v0, 0x2000
	v_mov_b32_e32 v1, s3
	global_atomic_add v0, v1, s[6:7] offset:1024

; __device__ __forceinline__ unsigned xb_ld(unsigned* p)              { return __hip_atomic_load(p, __ATOMIC_RELAXED, __HIP_MEMORY_SCOPE_AGENT); }
; __device__ __forceinline__ unsigned xb_add(unsigned* p, unsigned v) { return __hip_atomic_fetch_add(p, v, __ATOMIC_RELAXED, __HIP_MEMORY_SCOPE_AGENT); }
; #define XB_SPIN(cond, bar) do { unsigned _sp = 0; while (cond) { __builtin_amdgcn_s_sleep(1); \
;     if ((++_sp & 255u) == 0u) { if (xb_ld(&(bar)[XB_TMO])) break; if (_sp > XB_SPIN_CAP) { atomicAdd(&(bar)[XB_TMO], 1u); break; } } } } while (0)
; __device__ __forceinline__ void xcd_barrier(const XcdBarrier& b, bool leader) {
;     ...
;         if (nloc == 0u) { xcd_barrier_complete(bar, b.x, nloc, nx); b.st[0] = nloc; b.st[1] = nx; }
;         const unsigned old = xb_add(&bar[XB_XSUB(b.x)], 1u);
;         const unsigned gen = old / nloc;
;         if (old + 1u == (gen + 1u) * nloc) {
;             __builtin_amdgcn_fence(__ATOMIC_RELEASE, "agent");
;             asm volatile("s_waitcnt vmcnt(0)" ::: "memory");
;             const unsigned og = xb_add(&bar[XB_TOP], 1u);
;             const unsigned tg = og / nx;
;             if (og + 1u == (tg + 1u) * nx) xb_add(&bar[XB_TOPGEN], 1u);
;             else XB_SPIN(xb_ld(&bar[XB_TOPGEN]) == tg, bar);
;             __builtin_amdgcn_fence(__ATOMIC_ACQUIRE, "agent");
;             xb_add(&bar[XB_XGEN(b.x)], 1u);
;             asm volatile("s_waitcnt vmcnt(0)" ::: "memory");
;         } else {
;             XB_SPIN(xb_ld(&bar[XB_XGEN(b.x)]) == gen, bar);
.LBB0_2150:
	s_or_b64 exec, exec, s[12:13]
	v_cvt_f32_u32_e32 v4, v2
	s_waitcnt vmcnt(0)
	v_readfirstlane_b32 s3, v3
	v_sub_u32_e32 v3, 0, v2
	v_rcp_iflag_f32_e32 v4, v4
	v_add_u32_e32 v5, s3, v1
	v_mul_f32_e32 v4, 0x4f7ffffe, v4
	v_cvt_u32_f32_e32 v4, v4
	v_mul_lo_u32 v1, v3, v4
	v_mul_hi_u32 v1, v4, v1
	v_add_u32_e32 v1, v4, v1
	v_mul_hi_u32 v1, v5, v1
	v_mul_lo_u32 v3, v1, v2
	v_sub_u32_e32 v3, v5, v3
	v_add_u32_e32 v4, 1, v1
	v_cmp_ge_u32_e32 vcc, v3, v2
	s_nop 1
	v_cndmask_b32_e32 v1, v1, v4, vcc
	v_sub_u32_e32 v4, v3, v2
	v_cndmask_b32_e32 v3, v3, v4, vcc
	v_add_u32_e32 v4, 1, v1
	v_cmp_ge_u32_e32 vcc, v3, v2
	v_add_u32_e32 v3, 1, v5
	s_nop 0
	v_cndmask_b32_e32 v1, v1, v4, vcc
	v_mul_lo_u32 v4, v2, v1
	v_add_u32_e32 v2, v4, v2
	v_cmp_ne_u32_e32 vcc, v3, v2
	s_and_saveexec_b64 s[10:11], vcc
	s_xor_b64 s[10:11], exec, s[10:11]
	s_cbranch_execz .LBB0_2164
	buffer_inv sc1
	s_waitcnt lgkmcnt(0)
	v_mov_b32_e32 v0, 0x2000
	global_load_dword v0, v0, s[6:7] offset:1024 sc1
	s_add_u32 s14, s6, 0x2400
	s_addc_u32 s15, s7, 0
	s_waitcnt vmcnt(0)
	v_cmp_eq_u32_e32 vcc, v0, v1
	s_and_saveexec_b64 s[12:13], vcc
	s_cbranch_execz .LBB0_2163
	s_mov_b32 s3, 1
	s_mov_b64 s[16:17], 0
	v_mov_b32_e32 v0, 0
	s_branch .LBB0_2154

; __device__ __forceinline__ unsigned xb_ld(unsigned* p)              { return __hip_atomic_load(p, __ATOMIC_RELAXED, __HIP_MEMORY_SCOPE_AGENT); }
; #define XB_SPIN(cond, bar) do { unsigned _sp = 0; while (cond) { __builtin_amdgcn_s_sleep(1); \
;     if ((++_sp & 255u) == 0u) { if (xb_ld(&(bar)[XB_TMO])) break; if (_sp > XB_SPIN_CAP) { atomicAdd(&(bar)[XB_TMO], 1u); break; } } } } while (0)
; __device__ __forceinline__ void xcd_barrier(const XcdBarrier& b, bool leader) {
;     ...
;             XB_SPIN(xb_ld(&bar[XB_XGEN(b.x)]) == gen, bar);
;             __builtin_amdgcn_fence(__ATOMIC_ACQUIRE, "agent");
;             asm volatile("s_waitcnt vmcnt(0)" ::: "memory");
.LBB0_2163:
	s_or_b64 exec, exec, s[12:13]
	s_waitcnt vmcnt(0)
	s_waitcnt vmcnt(0)

; __device__ __forceinline__ unsigned xb_ld(unsigned* p)              { return __hip_atomic_load(p, __ATOMIC_RELAXED, __HIP_MEMORY_SCOPE_AGENT); }
; __device__ __forceinline__ unsigned xb_add(unsigned* p, unsigned v) { return __hip_atomic_fetch_add(p, v, __ATOMIC_RELAXED, __HIP_MEMORY_SCOPE_AGENT); }
; #define XB_SPIN(cond, bar) do { unsigned _sp = 0; while (cond) { __builtin_amdgcn_s_sleep(1); \
;     if ((++_sp & 255u) == 0u) { if (xb_ld(&(bar)[XB_TMO])) break; if (_sp > XB_SPIN_CAP) { atomicAdd(&(bar)[XB_TMO], 1u); break; } } } } while (0)
; __device__ __forceinline__ void xcd_barrier(const XcdBarrier& b, bool leader) {
;     ...
;             const unsigned og = xb_add(&bar[XB_TOP], 1u);
;             const unsigned tg = og / nx;
;             if (og + 1u == (tg + 1u) * nx) xb_add(&bar[XB_TOPGEN], 1u);
;             else XB_SPIN(xb_ld(&bar[XB_TOPGEN]) == tg, bar);
.LBB0_2167:
	s_or_b64 exec, exec, s[12:13]
	buffer_inv sc1
	v_cvt_f32_u32_e32 v3, v0
	s_waitcnt vmcnt(0)
	v_readfirstlane_b32 s3, v2
	s_add_u32 s12, s76, 0x3500
	s_addc_u32 s13, s77, 0
	v_rcp_iflag_f32_e32 v3, v3
	v_add_u32_e32 v1, s3, v1
	v_add_u32_e32 v4, 1, v1
	s_mov_b64 s[14:15], -1
	v_mul_f32_e32 v2, 0x4f7ffffe, v3
	v_cvt_u32_f32_e32 v2, v2
	v_sub_u32_e32 v3, 0, v0
	v_mul_lo_u32 v3, v3, v2
	v_mul_hi_u32 v3, v2, v3
	v_add_u32_e32 v2, v2, v3
	v_mul_hi_u32 v2, v1, v2
	v_mul_lo_u32 v3, v2, v0
	v_sub_u32_e32 v1, v1, v3
	v_add_u32_e32 v5, 1, v2
	v_cmp_ge_u32_e32 vcc, v1, v0
	v_sub_u32_e32 v3, v1, v0
	s_nop 0
	v_cndmask_b32_e32 v2, v2, v5, vcc
	v_cndmask_b32_e32 v1, v1, v3, vcc
	v_add_u32_e32 v3, 1, v2
	v_cmp_ge_u32_e32 vcc, v1, v0
	s_nop 1
	v_cndmask_b32_e32 v2, v2, v3, vcc
	v_mul_lo_u32 v1, v0, v2
	v_add_u32_e32 v0, v1, v0
	v_cmp_ne_u32_e32 vcc, v4, v0
	v_mov_b64_e32 v[0:1], s[12:13]
	s_and_saveexec_b64 s[10:11], vcc
	s_cbranch_execz .LBB0_2179
	v_mov_b32_e32 v0, 0
	global_load_dword v1, v0, s[12:13] sc1
	s_mov_b64 s[18:19], 0
	s_waitcnt vmcnt(0)
	v_cmp_eq_u32_e32 vcc, v1, v2
	s_and_saveexec_b64 s[16:17], vcc
	s_cbranch_execz .LBB0_2178
	s_add_u32 s14, s76, 0x200
	s_addc_u32 s15, s77, 0
	s_mov_b32 s3, 1
	s_branch .LBB0_2171

; __device__ __forceinline__ unsigned xb_add(unsigned* p, unsigned v) { return __hip_atomic_fetch_add(p, v, __ATOMIC_RELAXED, __HIP_MEMORY_SCOPE_AGENT); }
; __device__ __forceinline__ void xcd_barrier(const XcdBarrier& b, bool leader) {
;     ...
;             __builtin_amdgcn_fence(__ATOMIC_ACQUIRE, "agent");
;             xb_add(&bar[XB_XGEN(b.x)], 1u);
.LBB0_2181:
	s_or_b64 exec, exec, s[10:11]
	s_mov_b64 s[10:11], exec
	v_mbcnt_lo_u32_b32 v0, s10, 0
	v_mbcnt_hi_u32_b32 v0, s11, v0
	v_cmp_eq_u32_e32 vcc, 0, v0
	s_waitcnt vmcnt(0)
	s_and_saveexec_b64 s[12:13], vcc
	s_cbranch_execz .LBB0_2183
	s_bcnt1_i32_b64 s3, s[10:11]
	v_mov_b32_e32 v0, 0x2000
	v_mov_b32_e32 v1, s3
	global_atomic_add v0, v1, s[6:7] offset:1024

; __device__ __forceinline__ unsigned xb_ld(unsigned* p)              { return __hip_atomic_load(p, __ATOMIC_RELAXED, __HIP_MEMORY_SCOPE_AGENT); }
; __device__ __forceinline__ unsigned xb_add(unsigned* p, unsigned v) { return __hip_atomic_fetch_add(p, v, __ATOMIC_RELAXED, __HIP_MEMORY_SCOPE_AGENT); }
; #define XB_SPIN(cond, bar) do { unsigned _sp = 0; while (cond) { __builtin_amdgcn_s_sleep(1); \
;     if ((++_sp & 255u) == 0u) { if (xb_ld(&(bar)[XB_TMO])) break; if (_sp > XB_SPIN_CAP) { atomicAdd(&(bar)[XB_TMO], 1u); break; } } } } while (0)
; __device__ __forceinline__ void xcd_barrier(const XcdBarrier& b, bool leader) {
;     ...
;         if (nloc == 0u) { xcd_barrier_complete(bar, b.x, nloc, nx); b.st[0] = nloc; b.st[1] = nx; }
;         const unsigned old = xb_add(&bar[XB_XSUB(b.x)], 1u);
;         const unsigned gen = old / nloc;
;         if (old + 1u == (gen + 1u) * nloc) {
;             __builtin_amdgcn_fence(__ATOMIC_RELEASE, "agent");
;             asm volatile("s_waitcnt vmcnt(0)" ::: "memory");
;             const unsigned og = xb_add(&bar[XB_TOP], 1u);
;             const unsigned tg = og / nx;
;             if (og + 1u == (tg + 1u) * nx) xb_add(&bar[XB_TOPGEN], 1u);
;             else XB_SPIN(xb_ld(&bar[XB_TOPGEN]) == tg, bar);
;             __builtin_amdgcn_fence(__ATOMIC_ACQUIRE, "agent");
;             xb_add(&bar[XB_XGEN(b.x)], 1u);
;             asm volatile("s_waitcnt vmcnt(0)" ::: "memory");
;         } else {
;             XB_SPIN(xb_ld(&bar[XB_XGEN(b.x)]) == gen, bar);
.LBB0_2386:
	s_or_b64 exec, exec, s[10:11]
	v_cvt_f32_u32_e32 v4, v2
	s_waitcnt vmcnt(0)
	v_readfirstlane_b32 s6, v3
	v_sub_u32_e32 v3, 0, v2
	v_rcp_iflag_f32_e32 v4, v4
	v_add_u32_e32 v5, s6, v1
	v_mul_f32_e32 v4, 0x4f7ffffe, v4
	v_cvt_u32_f32_e32 v4, v4
	v_mul_lo_u32 v1, v3, v4
	v_mul_hi_u32 v1, v4, v1
	v_add_u32_e32 v1, v4, v1
	v_mul_hi_u32 v1, v5, v1
	v_mul_lo_u32 v3, v1, v2
	v_sub_u32_e32 v3, v5, v3
	v_add_u32_e32 v4, 1, v1
	v_cmp_ge_u32_e32 vcc, v3, v2
	s_nop 1
	v_cndmask_b32_e32 v1, v1, v4, vcc
	v_sub_u32_e32 v4, v3, v2
	v_cndmask_b32_e32 v3, v3, v4, vcc
	v_add_u32_e32 v4, 1, v1
	v_cmp_ge_u32_e32 vcc, v3, v2
	v_add_u32_e32 v3, 1, v5
	s_nop 0
	v_cndmask_b32_e32 v1, v1, v4, vcc
	v_mul_lo_u32 v4, v2, v1
	v_add_u32_e32 v2, v4, v2
	v_cmp_ne_u32_e32 vcc, v3, v2
	s_and_saveexec_b64 s[6:7], vcc
	s_xor_b64 s[6:7], exec, s[6:7]
	s_cbranch_execz .LBB0_2400
	buffer_inv sc1
	s_waitcnt lgkmcnt(0)
	v_mov_b32_e32 v0, 0x2000
	global_load_dword v0, v0, s[4:5] offset:1024 sc1
	s_add_u32 s12, s4, 0x2400
	s_addc_u32 s13, s5, 0
	s_waitcnt vmcnt(0)
	v_cmp_eq_u32_e32 vcc, v0, v1
	s_and_saveexec_b64 s[10:11], vcc
	s_cbranch_execz .LBB0_2399
	s_mov_b32 s24, 1
	s_mov_b64 s[14:15], 0
	v_mov_b32_e32 v0, 0
	s_branch .LBB0_2390

; __device__ __forceinline__ unsigned xb_ld(unsigned* p)              { return __hip_atomic_load(p, __ATOMIC_RELAXED, __HIP_MEMORY_SCOPE_AGENT); }
; __device__ __forceinline__ unsigned xb_add(unsigned* p, unsigned v) { return __hip_atomic_fetch_add(p, v, __ATOMIC_RELAXED, __HIP_MEMORY_SCOPE_AGENT); }
; #define XB_SPIN(cond, bar) do { unsigned _sp = 0; while (cond) { __builtin_amdgcn_s_sleep(1); \
;     if ((++_sp & 255u) == 0u) { if (xb_ld(&(bar)[XB_TMO])) break; if (_sp > XB_SPIN_CAP) { atomicAdd(&(bar)[XB_TMO], 1u); break; } } } } while (0)
; __device__ __forceinline__ void xcd_barrier(const XcdBarrier& b, bool leader) {
;     ...
;             const unsigned og = xb_add(&bar[XB_TOP], 1u);
;             const unsigned tg = og / nx;
;             if (og + 1u == (tg + 1u) * nx) xb_add(&bar[XB_TOPGEN], 1u);
;             else XB_SPIN(xb_ld(&bar[XB_TOPGEN]) == tg, bar);
.LBB0_2403:
	s_or_b64 exec, exec, s[10:11]
	buffer_inv sc1
	v_cvt_f32_u32_e32 v3, v0
	s_waitcnt vmcnt(0)
	v_readfirstlane_b32 s6, v2
	s_add_u32 s10, s76, 0x3500
	s_addc_u32 s11, s77, 0
	v_rcp_iflag_f32_e32 v3, v3
	v_add_u32_e32 v1, s6, v1
	v_add_u32_e32 v4, 1, v1
	s_mov_b64 s[12:13], -1
	v_mul_f32_e32 v2, 0x4f7ffffe, v3
	v_cvt_u32_f32_e32 v2, v2
	v_sub_u32_e32 v3, 0, v0
	v_mul_lo_u32 v3, v3, v2
	v_mul_hi_u32 v3, v2, v3
	v_add_u32_e32 v2, v2, v3
	v_mul_hi_u32 v2, v1, v2
	v_mul_lo_u32 v3, v2, v0
	v_sub_u32_e32 v1, v1, v3
	v_add_u32_e32 v5, 1, v2
	v_cmp_ge_u32_e32 vcc, v1, v0
	v_sub_u32_e32 v3, v1, v0
	s_nop 0
	v_cndmask_b32_e32 v2, v2, v5, vcc
	v_cndmask_b32_e32 v1, v1, v3, vcc
	v_add_u32_e32 v3, 1, v2
	v_cmp_ge_u32_e32 vcc, v1, v0
	s_nop 1
	v_cndmask_b32_e32 v2, v2, v3, vcc
	v_mul_lo_u32 v1, v0, v2
	v_add_u32_e32 v0, v1, v0
	v_cmp_ne_u32_e32 vcc, v4, v0
	v_mov_b64_e32 v[0:1], s[10:11]
	s_and_saveexec_b64 s[6:7], vcc
	s_cbranch_execz .LBB0_2415
	v_mov_b32_e32 v0, 0
	global_load_dword v1, v0, s[10:11] sc1
	s_mov_b64 s[16:17], 0
	s_waitcnt vmcnt(0)
	v_cmp_eq_u32_e32 vcc, v1, v2
	s_and_saveexec_b64 s[14:15], vcc
	s_cbranch_execz .LBB0_2414
	s_add_u32 s12, s76, 0x200
	s_addc_u32 s13, s77, 0
	s_mov_b32 s26, 1
	s_branch .LBB0_2407

; __device__ __forceinline__ unsigned xb_add(unsigned* p, unsigned v) { return __hip_atomic_fetch_add(p, v, __ATOMIC_RELAXED, __HIP_MEMORY_SCOPE_AGENT); }
; __device__ __forceinline__ void xcd_barrier(const XcdBarrier& b, bool leader) {
;     ...
;             __builtin_amdgcn_fence(__ATOMIC_ACQUIRE, "agent");
;             xb_add(&bar[XB_XGEN(b.x)], 1u);
.LBB0_2417:
	s_or_b64 exec, exec, s[6:7]
	s_mov_b64 s[6:7], exec
	v_mbcnt_lo_u32_b32 v0, s6, 0
	v_mbcnt_hi_u32_b32 v0, s7, v0
	v_cmp_eq_u32_e32 vcc, 0, v0
	s_waitcnt vmcnt(0)
	s_and_saveexec_b64 s[10:11], vcc
	s_cbranch_execz .LBB0_2419
	s_bcnt1_i32_b64 s6, s[6:7]
	v_mov_b32_e32 v0, 0x2000
	v_mov_b32_e32 v1, s6
	global_atomic_add v0, v1, s[4:5] offset:1024
